# in-projection GEMM epilogue rewritten: permlane16_swap merge + dwordx4 bf16 stores
# speedup vs baseline: 1.0653x; 1.0202x over previous
; template <class AP, class BP, class Epi>
; DI void mfma_gemm_big_tile(const AP& aptr, const BP& bptr, int m0, int n0, int K, const Epi& epi, bf16* lds) {
;     ...
; #pragma unroll
;   for (int i = 0; i < 8; ++i)
; #pragma unroll
;     for (int j = 0; j < 4; ++j) epi(m0 + wm + 16 * i + l16, n0 + wn + 16 * j + 4 * lq, acc[i][j]);
.LBB0_247:
	v_and_b32_e32 v131, 15, v172
	v_bfe_u32 v130, v172, 4, 2
	s_add_i32 s0, s10, s17
	s_add_i32 s1, s11, s12
	v_add_u32_e32 v131, s0, v131
	v_and_b32_e32 v132, 1, v130
	v_lshrrev_b32_e32 v130, 1, v130
	v_lshlrev_b32_e32 v132, 4, v132
	v_lshl_add_u32 v130, v130, 3, v132
	v_add_u32_e32 v130, s1, v130
	v_mul_u32_u24_e32 v131, 0x1400, v131
	v_lshl_add_u32 v133, v130, 1, v131
	v_cvt_pk_bf16_f32 v216, v126, v127
	v_cvt_pk_bf16_f32 v217, v128, v129
	v_cvt_pk_bf16_f32 v218, v122, v123
	v_cvt_pk_bf16_f32 v219, v124, v125
	s_nop 1
	v_permlane16_swap_b32_e32 v216, v218
	v_permlane16_swap_b32_e32 v217, v219
	global_store_dwordx4 v133, v[216:219], s[62:63] offset:0
	v_cvt_pk_bf16_f32 v220, v118, v119
	v_cvt_pk_bf16_f32 v221, v120, v121
	v_cvt_pk_bf16_f32 v222, v114, v115
	v_cvt_pk_bf16_f32 v223, v116, v117
	s_nop 1
	v_permlane16_swap_b32_e32 v220, v222
	v_permlane16_swap_b32_e32 v221, v223
	global_store_dwordx4 v133, v[220:223], s[62:63] offset:64
	v_add_u32_e32 v133, 0x14000, v133
	v_cvt_pk_bf16_f32 v224, v110, v111
	v_cvt_pk_bf16_f32 v225, v112, v113
	v_cvt_pk_bf16_f32 v226, v106, v107
	v_cvt_pk_bf16_f32 v227, v108, v109
	s_nop 1
	v_permlane16_swap_b32_e32 v224, v226
	v_permlane16_swap_b32_e32 v225, v227
	global_store_dwordx4 v133, v[224:227], s[62:63] offset:0
	v_cvt_pk_bf16_f32 v228, v102, v103
	v_cvt_pk_bf16_f32 v229, v104, v105
	v_cvt_pk_bf16_f32 v230, v98, v99
	v_cvt_pk_bf16_f32 v231, v100, v101
	s_nop 1
	v_permlane16_swap_b32_e32 v228, v230
	v_permlane16_swap_b32_e32 v229, v231
	global_store_dwordx4 v133, v[228:231], s[62:63] offset:64
	v_add_u32_e32 v133, 0x14000, v133
	v_cvt_pk_bf16_f32 v232, v94, v95
	v_cvt_pk_bf16_f32 v233, v96, v97
	v_cvt_pk_bf16_f32 v234, v90, v91
	v_cvt_pk_bf16_f32 v235, v92, v93
	s_nop 1
	v_permlane16_swap_b32_e32 v232, v234
	v_permlane16_swap_b32_e32 v233, v235
	global_store_dwordx4 v133, v[232:235], s[62:63] offset:0
	v_cvt_pk_bf16_f32 v236, v86, v87
	v_cvt_pk_bf16_f32 v237, v88, v89
	v_cvt_pk_bf16_f32 v238, v82, v83
	v_cvt_pk_bf16_f32 v239, v84, v85
	s_nop 1
	v_permlane16_swap_b32_e32 v236, v238
	v_permlane16_swap_b32_e32 v237, v239
	global_store_dwordx4 v133, v[236:239], s[62:63] offset:64
	v_add_u32_e32 v133, 0x14000, v133
	v_cvt_pk_bf16_f32 v240, v78, v79
	v_cvt_pk_bf16_f32 v241, v80, v81
	v_cvt_pk_bf16_f32 v242, v74, v75
	v_cvt_pk_bf16_f32 v243, v76, v77
	s_nop 1
	v_permlane16_swap_b32_e32 v240, v242
	v_permlane16_swap_b32_e32 v241, v243
	global_store_dwordx4 v133, v[240:243], s[62:63] offset:0
	v_cvt_pk_bf16_f32 v244, v70, v71
	v_cvt_pk_bf16_f32 v245, v72, v73
	v_cvt_pk_bf16_f32 v246, v66, v67
	v_cvt_pk_bf16_f32 v247, v68, v69
	s_nop 1
	v_permlane16_swap_b32_e32 v244, v246
	v_permlane16_swap_b32_e32 v245, v247
	global_store_dwordx4 v133, v[244:247], s[62:63] offset:64
	v_add_u32_e32 v133, 0x14000, v133
	v_cvt_pk_bf16_f32 v216, v62, v63
	v_cvt_pk_bf16_f32 v217, v64, v65
	v_cvt_pk_bf16_f32 v218, v58, v59
	v_cvt_pk_bf16_f32 v219, v60, v61
	s_nop 1
	v_permlane16_swap_b32_e32 v216, v218
	v_permlane16_swap_b32_e32 v217, v219
	global_store_dwordx4 v133, v[216:219], s[62:63] offset:0
	v_cvt_pk_bf16_f32 v220, v54, v55
	v_cvt_pk_bf16_f32 v221, v56, v57
	v_cvt_pk_bf16_f32 v222, v50, v51
	v_cvt_pk_bf16_f32 v223, v52, v53
	s_nop 1
	v_permlane16_swap_b32_e32 v220, v222
	v_permlane16_swap_b32_e32 v221, v223
	global_store_dwordx4 v133, v[220:223], s[62:63] offset:64
	v_add_u32_e32 v133, 0x14000, v133
	v_cvt_pk_bf16_f32 v224, v46, v47
	v_cvt_pk_bf16_f32 v225, v48, v49
	v_cvt_pk_bf16_f32 v226, v42, v43
	v_cvt_pk_bf16_f32 v227, v44, v45
	s_nop 1
	v_permlane16_swap_b32_e32 v224, v226
	v_permlane16_swap_b32_e32 v225, v227
	global_store_dwordx4 v133, v[224:227], s[62:63] offset:0
	v_cvt_pk_bf16_f32 v228, v38, v39
	v_cvt_pk_bf16_f32 v229, v40, v41
	v_cvt_pk_bf16_f32 v230, v34, v35
	v_cvt_pk_bf16_f32 v231, v36, v37
	s_nop 1
	v_permlane16_swap_b32_e32 v228, v230
	v_permlane16_swap_b32_e32 v229, v231
	global_store_dwordx4 v133, v[228:231], s[62:63] offset:64
	v_add_u32_e32 v133, 0x14000, v133
	v_cvt_pk_bf16_f32 v232, v30, v31
	v_cvt_pk_bf16_f32 v233, v32, v33
	v_cvt_pk_bf16_f32 v234, v26, v27
	v_cvt_pk_bf16_f32 v235, v28, v29
	s_nop 1
	v_permlane16_swap_b32_e32 v232, v234
	v_permlane16_swap_b32_e32 v233, v235
	global_store_dwordx4 v133, v[232:235], s[62:63] offset:0
	v_cvt_pk_bf16_f32 v236, v22, v23
	v_cvt_pk_bf16_f32 v237, v24, v25
	v_cvt_pk_bf16_f32 v238, v18, v19
	v_cvt_pk_bf16_f32 v239, v20, v21
	s_nop 1
	v_permlane16_swap_b32_e32 v236, v238
	v_permlane16_swap_b32_e32 v237, v239
	global_store_dwordx4 v133, v[236:239], s[62:63] offset:64
	v_add_u32_e32 v133, 0x14000, v133
	v_cvt_pk_bf16_f32 v240, v14, v15
	v_cvt_pk_bf16_f32 v241, v16, v17
	v_cvt_pk_bf16_f32 v242, v10, v11
	v_cvt_pk_bf16_f32 v243, v12, v13
	s_nop 1
	v_permlane16_swap_b32_e32 v240, v242
	v_permlane16_swap_b32_e32 v241, v243
	global_store_dwordx4 v133, v[240:243], s[62:63] offset:0
	v_cvt_pk_bf16_f32 v244, v6, v7
	v_cvt_pk_bf16_f32 v245, v8, v9
	v_cvt_pk_bf16_f32 v246, v2, v3
	v_cvt_pk_bf16_f32 v247, v4, v5
	s_nop 1
	v_permlane16_swap_b32_e32 v244, v246
	v_permlane16_swap_b32_e32 v245, v247
	global_store_dwordx4 v133, v[244:247], s[62:63] offset:64
	s_add_i32 s9, s9, s41
	s_cmp_ge_i32 s9, s8
	s_waitcnt vmcnt(0) lgkmcnt(0)
	s_barrier
	s_cbranch_scc1 .LBB0_256

; template <class AP, class BP, class Epi>
; DI void mfma_gemm_big_tile(const AP& aptr, const BP& bptr, int m0, int n0, int K, const Epi& epi, bf16* lds) {
;     ...
; #pragma unroll
;   for (int i = 0; i < 8; ++i)
; #pragma unroll
;     for (int j = 0; j < 4; ++j) epi(m0 + wm + 16 * i + l16, n0 + wn + 16 * j + 4 * lq, acc[i][j]);
;   asm volatile("s_waitcnt vmcnt(0)" ::: "memory");
;   __syncthreads();
.LBB0_507:
	v_and_b32_e32 v131, 15, v172
	v_bfe_u32 v130, v172, 4, 2
	s_add_i32 s0, s10, s16
	s_add_i32 s1, s11, s12
	v_add_u32_e32 v131, s0, v131
	v_and_b32_e32 v132, 1, v130
	v_lshrrev_b32_e32 v130, 1, v130
	v_lshlrev_b32_e32 v132, 4, v132
	v_lshl_add_u32 v130, v130, 3, v132
	v_add_u32_e32 v130, s1, v130
	v_mul_u32_u24_e32 v131, 0x1400, v131
	v_lshl_add_u32 v133, v130, 1, v131
	v_cvt_pk_bf16_f32 v216, v126, v127
	v_cvt_pk_bf16_f32 v217, v128, v129
	v_cvt_pk_bf16_f32 v218, v122, v123
	v_cvt_pk_bf16_f32 v219, v124, v125
	s_nop 1
	v_permlane16_swap_b32_e32 v216, v218
	v_permlane16_swap_b32_e32 v217, v219
	global_store_dwordx4 v133, v[216:219], s[62:63] offset:0
	v_cvt_pk_bf16_f32 v220, v118, v119
	v_cvt_pk_bf16_f32 v221, v120, v121
	v_cvt_pk_bf16_f32 v222, v114, v115
	v_cvt_pk_bf16_f32 v223, v116, v117
	s_nop 1
	v_permlane16_swap_b32_e32 v220, v222
	v_permlane16_swap_b32_e32 v221, v223
	global_store_dwordx4 v133, v[220:223], s[62:63] offset:64
	v_add_u32_e32 v133, 0x14000, v133
	v_cvt_pk_bf16_f32 v224, v110, v111
	v_cvt_pk_bf16_f32 v225, v112, v113
	v_cvt_pk_bf16_f32 v226, v106, v107
	v_cvt_pk_bf16_f32 v227, v108, v109
	s_nop 1
	v_permlane16_swap_b32_e32 v224, v226
	v_permlane16_swap_b32_e32 v225, v227
	global_store_dwordx4 v133, v[224:227], s[62:63] offset:0
	v_cvt_pk_bf16_f32 v228, v102, v103
	v_cvt_pk_bf16_f32 v229, v104, v105
	v_cvt_pk_bf16_f32 v230, v98, v99
	v_cvt_pk_bf16_f32 v231, v100, v101
	s_nop 1
	v_permlane16_swap_b32_e32 v228, v230
	v_permlane16_swap_b32_e32 v229, v231
	global_store_dwordx4 v133, v[228:231], s[62:63] offset:64
	v_add_u32_e32 v133, 0x14000, v133
	v_cvt_pk_bf16_f32 v232, v94, v95
	v_cvt_pk_bf16_f32 v233, v96, v97
	v_cvt_pk_bf16_f32 v234, v90, v91
	v_cvt_pk_bf16_f32 v235, v92, v93
	s_nop 1
	v_permlane16_swap_b32_e32 v232, v234
	v_permlane16_swap_b32_e32 v233, v235
	global_store_dwordx4 v133, v[232:235], s[62:63] offset:0
	v_cvt_pk_bf16_f32 v236, v86, v87
	v_cvt_pk_bf16_f32 v237, v88, v89
	v_cvt_pk_bf16_f32 v238, v82, v83
	v_cvt_pk_bf16_f32 v239, v84, v85
	s_nop 1
	v_permlane16_swap_b32_e32 v236, v238
	v_permlane16_swap_b32_e32 v237, v239
	global_store_dwordx4 v133, v[236:239], s[62:63] offset:64
	v_add_u32_e32 v133, 0x14000, v133
	v_cvt_pk_bf16_f32 v240, v78, v79
	v_cvt_pk_bf16_f32 v241, v80, v81
	v_cvt_pk_bf16_f32 v242, v74, v75
	v_cvt_pk_bf16_f32 v243, v76, v77
	s_nop 1
	v_permlane16_swap_b32_e32 v240, v242
	v_permlane16_swap_b32_e32 v241, v243
	global_store_dwordx4 v133, v[240:243], s[62:63] offset:0
	v_cvt_pk_bf16_f32 v244, v70, v71
	v_cvt_pk_bf16_f32 v245, v72, v73
	v_cvt_pk_bf16_f32 v246, v66, v67
	v_cvt_pk_bf16_f32 v247, v68, v69
	s_nop 1
	v_permlane16_swap_b32_e32 v244, v246
	v_permlane16_swap_b32_e32 v245, v247
	global_store_dwordx4 v133, v[244:247], s[62:63] offset:64
	v_add_u32_e32 v133, 0x14000, v133
	v_cvt_pk_bf16_f32 v216, v62, v63
	v_cvt_pk_bf16_f32 v217, v64, v65
	v_cvt_pk_bf16_f32 v218, v58, v59
	v_cvt_pk_bf16_f32 v219, v60, v61
	s_nop 1
	v_permlane16_swap_b32_e32 v216, v218
	v_permlane16_swap_b32_e32 v217, v219
	global_store_dwordx4 v133, v[216:219], s[62:63] offset:0
	v_cvt_pk_bf16_f32 v220, v54, v55
	v_cvt_pk_bf16_f32 v221, v56, v57
	v_cvt_pk_bf16_f32 v222, v50, v51
	v_cvt_pk_bf16_f32 v223, v52, v53
	s_nop 1
	v_permlane16_swap_b32_e32 v220, v222
	v_permlane16_swap_b32_e32 v221, v223
	global_store_dwordx4 v133, v[220:223], s[62:63] offset:64
	v_add_u32_e32 v133, 0x14000, v133
	v_cvt_pk_bf16_f32 v224, v46, v47
	v_cvt_pk_bf16_f32 v225, v48, v49
	v_cvt_pk_bf16_f32 v226, v42, v43
	v_cvt_pk_bf16_f32 v227, v44, v45
	s_nop 1
	v_permlane16_swap_b32_e32 v224, v226
	v_permlane16_swap_b32_e32 v225, v227
	global_store_dwordx4 v133, v[224:227], s[62:63] offset:0
	v_cvt_pk_bf16_f32 v228, v38, v39
	v_cvt_pk_bf16_f32 v229, v40, v41
	v_cvt_pk_bf16_f32 v230, v34, v35
	v_cvt_pk_bf16_f32 v231, v36, v37
	s_nop 1
	v_permlane16_swap_b32_e32 v228, v230
	v_permlane16_swap_b32_e32 v229, v231
	global_store_dwordx4 v133, v[228:231], s[62:63] offset:64
	v_add_u32_e32 v133, 0x14000, v133
	v_cvt_pk_bf16_f32 v232, v30, v31
	v_cvt_pk_bf16_f32 v233, v32, v33
	v_cvt_pk_bf16_f32 v234, v26, v27
	v_cvt_pk_bf16_f32 v235, v28, v29
	s_nop 1
	v_permlane16_swap_b32_e32 v232, v234
	v_permlane16_swap_b32_e32 v233, v235
	global_store_dwordx4 v133, v[232:235], s[62:63] offset:0
	v_cvt_pk_bf16_f32 v236, v22, v23
	v_cvt_pk_bf16_f32 v237, v24, v25
	v_cvt_pk_bf16_f32 v238, v18, v19
	v_cvt_pk_bf16_f32 v239, v20, v21
	s_nop 1
	v_permlane16_swap_b32_e32 v236, v238
	v_permlane16_swap_b32_e32 v237, v239
	global_store_dwordx4 v133, v[236:239], s[62:63] offset:64
	v_add_u32_e32 v133, 0x14000, v133
	v_cvt_pk_bf16_f32 v240, v14, v15
	v_cvt_pk_bf16_f32 v241, v16, v17
	v_cvt_pk_bf16_f32 v242, v10, v11
	v_cvt_pk_bf16_f32 v243, v12, v13
	s_nop 1
	v_permlane16_swap_b32_e32 v240, v242
	v_permlane16_swap_b32_e32 v241, v243
	global_store_dwordx4 v133, v[240:243], s[62:63] offset:0
	v_cvt_pk_bf16_f32 v244, v6, v7
	v_cvt_pk_bf16_f32 v245, v8, v9
	v_cvt_pk_bf16_f32 v246, v2, v3
	v_cvt_pk_bf16_f32 v247, v4, v5
	s_nop 1
	v_permlane16_swap_b32_e32 v244, v246
	v_permlane16_swap_b32_e32 v245, v247
	global_store_dwordx4 v133, v[244:247], s[62:63] offset:64
	s_add_i32 s9, s9, s41
	s_cmp_ge_i32 s9, s8
	s_waitcnt vmcnt(0) lgkmcnt(0)
	s_barrier
	s_cbranch_scc1 .LBB0_516
